# P5 gate-merge epilogue: raised priority for one wave of each SIMD pair
# baseline (speedup 1.0000x reference)
.LBB0_2233:
	s_and_b64 vcc, exec, s[10:11]
	s_cbranch_vccz .Lp5prio_skip
	s_setprio 2

.LBB0_2267:
	s_waitcnt vmcnt(7)
	v_lshlrev_b32_e32 v98, 16, v128
	v_mul_f32_e32 v98, 0xbfb8aa3b, v98
	v_exp_f32_e32 v98, v98
	v_and_b32_e32 v128, 0xffff0000, v128
	v_lshlrev_b64 v[136:137], 11, v[134:135]
	v_lshlrev_b64 v[134:135], 11, v[138:139]
	v_add_f32_e32 v98, 1.0, v98
	v_mul_f32_e32 v128, 0xbfb8aa3b, v128
	v_lshlrev_b32_e32 v139, 16, v129
	v_rcp_f32_e32 v98, v98
	v_exp_f32_e32 v128, v128
	v_mul_f32_e32 v139, 0xbfb8aa3b, v139
	v_exp_f32_e32 v139, v139
	v_lshlrev_b32_e32 v138, 16, v90
	v_fmac_f32_e32 v138, v62, v98
	v_add_f32_e32 v62, 1.0, v128
	v_rcp_f32_e32 v62, v62
	v_add_f32_e32 v98, 1.0, v139
	v_rcp_f32_e32 v98, v98
	v_and_b32_e32 v90, 0xffff0000, v90
	v_fmac_f32_e32 v90, v63, v62
	v_lshlrev_b32_e32 v62, 16, v91
	v_and_b32_e32 v63, 0xffff0000, v129
	v_fmac_f32_e32 v62, v64, v98
	v_mul_f32_e32 v63, 0xbfb8aa3b, v63
	v_lshlrev_b32_e32 v64, 16, v130
	v_exp_f32_e32 v63, v63
	v_mul_f32_e32 v64, 0xbfb8aa3b, v64
	v_exp_f32_e32 v64, v64
	v_and_b32_e32 v98, 0xffff0000, v130
	v_add_f32_e32 v63, 1.0, v63
	v_rcp_f32_e32 v63, v63
	v_add_f32_e32 v64, 1.0, v64
	v_rcp_f32_e32 v64, v64
	v_mul_f32_e32 v98, 0xbfb8aa3b, v98
	v_exp_f32_e32 v98, v98
	v_and_b32_e32 v91, 0xffff0000, v91
	v_fmac_f32_e32 v91, v65, v63
	v_lshlrev_b32_e32 v63, 16, v92
	v_fmac_f32_e32 v63, v58, v64
	v_and_b32_e32 v64, 0xffff0000, v92
	v_and_b32_e32 v92, 0xffff0000, v131
	v_add_f32_e32 v58, 1.0, v98
	v_mul_f32_e32 v92, 0xbfb8aa3b, v92
	v_rcp_f32_e32 v58, v58
	v_lshlrev_b32_e32 v65, 16, v131
	v_exp_f32_e32 v92, v92
	v_mul_f32_e32 v65, 0xbfb8aa3b, v65
	v_exp_f32_e32 v65, v65
	v_fmac_f32_e32 v64, v59, v58
	v_add_f32_e32 v59, 1.0, v92
	v_rcp_f32_e32 v59, v59
	v_add_f32_e32 v58, 1.0, v65
	v_rcp_f32_e32 v58, v58
	v_and_b32_e32 v92, 0xffff0000, v93
	v_fmac_f32_e32 v92, v61, v59
	s_waitcnt vmcnt(6)
	v_lshlrev_b32_e32 v61, 16, v124
	v_lshlrev_b32_e32 v65, 16, v93
	v_mul_f32_e32 v61, 0xbfb8aa3b, v61
	v_fmac_f32_e32 v65, v60, v58
	v_cvt_pk_bf16_f32 v58, v138, v90
	v_cvt_pk_bf16_f32 v59, v62, v91
	v_cvt_pk_bf16_f32 v60, v63, v64
	v_exp_f32_e32 v64, v61
	v_lshlrev_b64 v[142:143], 11, v[132:133]
	v_lshl_add_u64 v[62:63], v[142:143], 1, v[218:219]
	v_cvt_pk_bf16_f32 v61, v65, v92
	global_store_dwordx4 v[62:63], v[58:61], off
	v_lshlrev_b64 v[132:133], 11, v[140:141]
	s_andn2_b64 vcc, exec, s[38:39]
	v_and_b32_e32 v60, 0xffff0000, v124
	v_add_f32_e32 v58, 1.0, v64
	v_mul_f32_e32 v60, 0xbfb8aa3b, v60
	v_lshlrev_b32_e32 v61, 16, v125
	v_rcp_f32_e32 v58, v58
	v_exp_f32_e32 v60, v60
	v_mul_f32_e32 v61, 0xbfb8aa3b, v61
	v_exp_f32_e32 v61, v61
	v_lshlrev_b32_e32 v59, 16, v120
	v_fmac_f32_e32 v59, v54, v58
	v_add_f32_e32 v54, 1.0, v60
	v_rcp_f32_e32 v54, v54
	v_add_f32_e32 v58, 1.0, v61
	v_rcp_f32_e32 v58, v58
	v_and_b32_e32 v60, 0xffff0000, v120
	v_fmac_f32_e32 v60, v55, v54
	v_lshlrev_b32_e32 v54, 16, v121
	v_and_b32_e32 v55, 0xffff0000, v125
	v_fmac_f32_e32 v54, v56, v58
	v_mul_f32_e32 v55, 0xbfb8aa3b, v55
	v_lshlrev_b32_e32 v56, 16, v126
	v_exp_f32_e32 v55, v55
	v_mul_f32_e32 v56, 0xbfb8aa3b, v56
	v_exp_f32_e32 v56, v56
	v_and_b32_e32 v61, 0xffff0000, v126
	v_add_f32_e32 v55, 1.0, v55
	v_rcp_f32_e32 v55, v55
	v_add_f32_e32 v56, 1.0, v56
	v_mul_f32_e32 v61, 0xbfb8aa3b, v61
	v_rcp_f32_e32 v56, v56
	v_exp_f32_e32 v61, v61
	v_and_b32_e32 v58, 0xffff0000, v121
	v_fmac_f32_e32 v58, v57, v55
	v_lshlrev_b32_e32 v55, 16, v122
	v_lshlrev_b32_e32 v57, 16, v127
	v_fmac_f32_e32 v55, v50, v56
	v_add_f32_e32 v50, 1.0, v61
	v_mul_f32_e32 v57, 0xbfb8aa3b, v57
	v_rcp_f32_e32 v50, v50
	v_exp_f32_e32 v57, v57
	v_and_b32_e32 v61, 0xffff0000, v127
	v_mul_f32_e32 v61, 0xbfb8aa3b, v61
	v_exp_f32_e32 v61, v61
	v_and_b32_e32 v56, 0xffff0000, v122
	v_fmac_f32_e32 v56, v51, v50
	v_add_f32_e32 v50, 1.0, v57
	v_rcp_f32_e32 v50, v50
	v_add_f32_e32 v51, 1.0, v61
	v_rcp_f32_e32 v51, v51
	v_lshlrev_b32_e32 v57, 16, v123
	v_fmac_f32_e32 v57, v52, v50
	s_waitcnt vmcnt(6)
	v_lshlrev_b32_e32 v52, 16, v116
	v_and_b32_e32 v61, 0xffff0000, v123
	v_mul_f32_e32 v52, 0xbfb8aa3b, v52
	v_fmac_f32_e32 v61, v53, v51
	v_cvt_pk_bf16_f32 v50, v59, v60
	v_cvt_pk_bf16_f32 v51, v54, v58
	v_exp_f32_e32 v54, v52
	v_cvt_pk_bf16_f32 v52, v55, v56
	v_cvt_pk_bf16_f32 v53, v57, v61
	global_store_dwordx4 v[62:63], v[50:53], off offset:256
	s_mov_b64 s[20:21], -1
	s_nop 0
	v_and_b32_e32 v52, 0xffff0000, v116
	v_add_f32_e32 v50, 1.0, v54
	v_mul_f32_e32 v52, 0xbfb8aa3b, v52
	v_lshlrev_b32_e32 v53, 16, v117
	v_rcp_f32_e32 v50, v50
	v_exp_f32_e32 v52, v52
	v_mul_f32_e32 v53, 0xbfb8aa3b, v53
	v_exp_f32_e32 v53, v53
	v_lshlrev_b32_e32 v51, 16, v112
	v_fmac_f32_e32 v51, v46, v50
	v_add_f32_e32 v46, 1.0, v52
	v_rcp_f32_e32 v46, v46
	v_add_f32_e32 v50, 1.0, v53
	v_rcp_f32_e32 v50, v50
	v_and_b32_e32 v52, 0xffff0000, v112
	v_fmac_f32_e32 v52, v47, v46
	v_lshlrev_b32_e32 v46, 16, v113
	v_and_b32_e32 v47, 0xffff0000, v117
	v_fmac_f32_e32 v46, v48, v50
	v_mul_f32_e32 v47, 0xbfb8aa3b, v47
	v_lshlrev_b32_e32 v48, 16, v118
	v_exp_f32_e32 v47, v47
	v_mul_f32_e32 v48, 0xbfb8aa3b, v48
	v_exp_f32_e32 v48, v48
	v_and_b32_e32 v53, 0xffff0000, v118
	v_add_f32_e32 v47, 1.0, v47
	v_rcp_f32_e32 v47, v47
	v_add_f32_e32 v48, 1.0, v48
	v_mul_f32_e32 v53, 0xbfb8aa3b, v53
	v_rcp_f32_e32 v48, v48
	v_exp_f32_e32 v53, v53
	v_and_b32_e32 v50, 0xffff0000, v113
	v_fmac_f32_e32 v50, v49, v47
	v_lshlrev_b32_e32 v47, 16, v114
	v_fmac_f32_e32 v47, v42, v48
	v_add_f32_e32 v42, 1.0, v53
	v_and_b32_e32 v53, 0xffff0000, v119
	v_mul_f32_e32 v53, 0xbfb8aa3b, v53
	v_rcp_f32_e32 v42, v42
	v_lshlrev_b32_e32 v49, 16, v119
	v_exp_f32_e32 v53, v53
	v_mul_f32_e32 v49, 0xbfb8aa3b, v49
	v_exp_f32_e32 v49, v49
	v_and_b32_e32 v48, 0xffff0000, v114
	v_fmac_f32_e32 v48, v43, v42
	v_add_f32_e32 v43, 1.0, v53
	v_rcp_f32_e32 v43, v43
	v_add_f32_e32 v42, 1.0, v49
	v_rcp_f32_e32 v42, v42
	v_and_b32_e32 v53, 0xffff0000, v115
	v_fmac_f32_e32 v53, v45, v43
	s_waitcnt vmcnt(6)
	v_lshlrev_b32_e32 v45, 16, v108
	v_lshlrev_b32_e32 v49, 16, v115
	v_mul_f32_e32 v45, 0xbfb8aa3b, v45
	v_fmac_f32_e32 v49, v44, v42
	v_cvt_pk_bf16_f32 v42, v51, v52
	v_cvt_pk_bf16_f32 v43, v46, v50
	v_cvt_pk_bf16_f32 v44, v47, v48
	v_exp_f32_e32 v48, v45
	v_lshl_add_u64 v[46:47], v[136:137], 1, v[218:219]
	v_cvt_pk_bf16_f32 v45, v49, v53
	global_store_dwordx4 v[46:47], v[42:45], off
	s_nop 1
	v_and_b32_e32 v44, 0xffff0000, v108
	v_add_f32_e32 v42, 1.0, v48
	v_mul_f32_e32 v44, 0xbfb8aa3b, v44
	v_lshlrev_b32_e32 v45, 16, v109
	v_rcp_f32_e32 v42, v42
	v_exp_f32_e32 v44, v44
	v_mul_f32_e32 v45, 0xbfb8aa3b, v45
	v_exp_f32_e32 v45, v45
	v_lshlrev_b32_e32 v43, 16, v104
	v_fmac_f32_e32 v43, v38, v42
	v_add_f32_e32 v38, 1.0, v44
	v_rcp_f32_e32 v38, v38
	v_add_f32_e32 v42, 1.0, v45
	v_rcp_f32_e32 v42, v42
	v_and_b32_e32 v44, 0xffff0000, v104
	v_fmac_f32_e32 v44, v39, v38
	v_lshlrev_b32_e32 v38, 16, v105
	v_and_b32_e32 v39, 0xffff0000, v109
	v_fmac_f32_e32 v38, v40, v42
	v_mul_f32_e32 v39, 0xbfb8aa3b, v39
	v_lshlrev_b32_e32 v40, 16, v110
	v_exp_f32_e32 v39, v39
	v_mul_f32_e32 v40, 0xbfb8aa3b, v40
	v_exp_f32_e32 v40, v40
	v_and_b32_e32 v45, 0xffff0000, v110
	v_add_f32_e32 v39, 1.0, v39
	v_rcp_f32_e32 v39, v39
	v_add_f32_e32 v40, 1.0, v40
	v_mul_f32_e32 v45, 0xbfb8aa3b, v45
	v_rcp_f32_e32 v40, v40
	v_exp_f32_e32 v45, v45
	v_and_b32_e32 v42, 0xffff0000, v105
	v_fmac_f32_e32 v42, v41, v39
	v_lshlrev_b32_e32 v39, 16, v106
	v_lshlrev_b32_e32 v41, 16, v111
	v_fmac_f32_e32 v39, v34, v40
	v_add_f32_e32 v34, 1.0, v45
	v_mul_f32_e32 v41, 0xbfb8aa3b, v41
	v_rcp_f32_e32 v34, v34
	v_exp_f32_e32 v41, v41
	v_and_b32_e32 v45, 0xffff0000, v111
	v_mul_f32_e32 v45, 0xbfb8aa3b, v45
	v_exp_f32_e32 v45, v45
	v_and_b32_e32 v40, 0xffff0000, v106
	v_fmac_f32_e32 v40, v35, v34
	v_add_f32_e32 v34, 1.0, v41
	v_rcp_f32_e32 v34, v34
	v_add_f32_e32 v35, 1.0, v45
	v_rcp_f32_e32 v35, v35
	v_lshlrev_b32_e32 v41, 16, v107
	v_fmac_f32_e32 v41, v36, v34
	s_waitcnt vmcnt(6)
	v_lshlrev_b32_e32 v36, 16, v100
	v_and_b32_e32 v45, 0xffff0000, v107
	v_mul_f32_e32 v36, 0xbfb8aa3b, v36
	v_fmac_f32_e32 v45, v37, v35
	v_cvt_pk_bf16_f32 v34, v43, v44
	v_cvt_pk_bf16_f32 v35, v38, v42
	v_exp_f32_e32 v38, v36
	v_cvt_pk_bf16_f32 v36, v39, v40
	v_cvt_pk_bf16_f32 v37, v41, v45
	global_store_dwordx4 v[46:47], v[34:37], off offset:256
	s_nop 1
	v_and_b32_e32 v36, 0xffff0000, v100
	v_add_f32_e32 v34, 1.0, v38
	v_mul_f32_e32 v36, 0xbfb8aa3b, v36
	v_lshlrev_b32_e32 v37, 16, v101
	v_rcp_f32_e32 v34, v34
	v_exp_f32_e32 v36, v36
	v_mul_f32_e32 v37, 0xbfb8aa3b, v37
	v_exp_f32_e32 v37, v37
	v_lshlrev_b32_e32 v35, 16, v94
	v_fmac_f32_e32 v35, v30, v34
	v_add_f32_e32 v30, 1.0, v36
	v_rcp_f32_e32 v30, v30
	v_add_f32_e32 v34, 1.0, v37
	v_rcp_f32_e32 v34, v34
	v_and_b32_e32 v36, 0xffff0000, v94
	v_fmac_f32_e32 v36, v31, v30
	v_lshlrev_b32_e32 v30, 16, v95
	v_and_b32_e32 v31, 0xffff0000, v101
	v_fmac_f32_e32 v30, v32, v34
	v_mul_f32_e32 v31, 0xbfb8aa3b, v31
	v_lshlrev_b32_e32 v32, 16, v102
	v_exp_f32_e32 v31, v31
	v_mul_f32_e32 v32, 0xbfb8aa3b, v32
	v_exp_f32_e32 v32, v32
	v_and_b32_e32 v37, 0xffff0000, v102
	v_add_f32_e32 v31, 1.0, v31
	v_rcp_f32_e32 v31, v31
	v_add_f32_e32 v32, 1.0, v32
	v_mul_f32_e32 v37, 0xbfb8aa3b, v37
	v_rcp_f32_e32 v32, v32
	v_exp_f32_e32 v37, v37
	v_and_b32_e32 v34, 0xffff0000, v95
	v_fmac_f32_e32 v34, v33, v31
	v_lshlrev_b32_e32 v31, 16, v96
	v_fmac_f32_e32 v31, v26, v32
	v_add_f32_e32 v26, 1.0, v37
	v_and_b32_e32 v37, 0xffff0000, v103
	v_mul_f32_e32 v37, 0xbfb8aa3b, v37
	v_rcp_f32_e32 v26, v26
	v_lshlrev_b32_e32 v33, 16, v103
	v_exp_f32_e32 v37, v37
	v_mul_f32_e32 v33, 0xbfb8aa3b, v33
	v_exp_f32_e32 v33, v33
	v_and_b32_e32 v32, 0xffff0000, v96
	v_fmac_f32_e32 v32, v27, v26
	v_add_f32_e32 v27, 1.0, v37
	v_rcp_f32_e32 v27, v27
	v_add_f32_e32 v26, 1.0, v33
	v_rcp_f32_e32 v26, v26
	v_and_b32_e32 v37, 0xffff0000, v97
	v_fmac_f32_e32 v37, v29, v27
	s_waitcnt vmcnt(6)
	v_lshlrev_b32_e32 v29, 16, v86
	v_lshlrev_b32_e32 v33, 16, v97
	v_mul_f32_e32 v29, 0xbfb8aa3b, v29
	v_fmac_f32_e32 v33, v28, v26
	v_cvt_pk_bf16_f32 v26, v35, v36
	v_cvt_pk_bf16_f32 v27, v30, v34
	v_cvt_pk_bf16_f32 v28, v31, v32
	v_exp_f32_e32 v32, v29
	v_lshl_add_u64 v[30:31], v[134:135], 1, v[218:219]
	v_cvt_pk_bf16_f32 v29, v33, v37
	global_store_dwordx4 v[30:31], v[26:29], off
	s_nop 1
	v_and_b32_e32 v28, 0xffff0000, v86
	v_add_f32_e32 v26, 1.0, v32
	v_mul_f32_e32 v28, 0xbfb8aa3b, v28
	v_lshlrev_b32_e32 v29, 16, v87
	v_rcp_f32_e32 v26, v26
	v_exp_f32_e32 v28, v28
	v_mul_f32_e32 v29, 0xbfb8aa3b, v29
	v_exp_f32_e32 v29, v29
	v_lshlrev_b32_e32 v27, 16, v82
	v_fmac_f32_e32 v27, v22, v26
	v_add_f32_e32 v22, 1.0, v28
	v_rcp_f32_e32 v22, v22
	v_add_f32_e32 v26, 1.0, v29
	v_rcp_f32_e32 v26, v26
	v_and_b32_e32 v28, 0xffff0000, v82
	v_fmac_f32_e32 v28, v23, v22
	v_lshlrev_b32_e32 v22, 16, v83
	v_and_b32_e32 v23, 0xffff0000, v87
	v_fmac_f32_e32 v22, v24, v26
	v_mul_f32_e32 v23, 0xbfb8aa3b, v23
	v_lshlrev_b32_e32 v24, 16, v88
	v_exp_f32_e32 v23, v23
	v_mul_f32_e32 v24, 0xbfb8aa3b, v24
	v_exp_f32_e32 v24, v24
	v_and_b32_e32 v29, 0xffff0000, v88
	v_add_f32_e32 v23, 1.0, v23
	v_rcp_f32_e32 v23, v23
	v_add_f32_e32 v24, 1.0, v24
	v_mul_f32_e32 v29, 0xbfb8aa3b, v29
	v_rcp_f32_e32 v24, v24
	v_exp_f32_e32 v29, v29
	v_and_b32_e32 v26, 0xffff0000, v83
	v_fmac_f32_e32 v26, v25, v23
	v_lshlrev_b32_e32 v23, 16, v84
	v_lshlrev_b32_e32 v25, 16, v89
	v_fmac_f32_e32 v23, v18, v24
	v_add_f32_e32 v18, 1.0, v29
	v_mul_f32_e32 v25, 0xbfb8aa3b, v25
	v_rcp_f32_e32 v18, v18
	v_exp_f32_e32 v25, v25
	v_and_b32_e32 v29, 0xffff0000, v89
	v_mul_f32_e32 v29, 0xbfb8aa3b, v29
	v_exp_f32_e32 v29, v29
	v_and_b32_e32 v24, 0xffff0000, v84
	v_fmac_f32_e32 v24, v19, v18
	v_add_f32_e32 v18, 1.0, v25
	v_rcp_f32_e32 v18, v18
	v_add_f32_e32 v19, 1.0, v29
	v_rcp_f32_e32 v19, v19
	v_lshlrev_b32_e32 v25, 16, v85
	v_fmac_f32_e32 v25, v20, v18
	s_waitcnt vmcnt(6)
	v_lshlrev_b32_e32 v20, 16, v78
	v_and_b32_e32 v29, 0xffff0000, v85
	v_mul_f32_e32 v20, 0xbfb8aa3b, v20
	v_fmac_f32_e32 v29, v21, v19
	v_cvt_pk_bf16_f32 v18, v27, v28
	v_cvt_pk_bf16_f32 v19, v22, v26
	v_exp_f32_e32 v22, v20
	v_cvt_pk_bf16_f32 v20, v23, v24
	v_cvt_pk_bf16_f32 v21, v25, v29
	global_store_dwordx4 v[30:31], v[18:21], off offset:256
	s_nop 1
	v_and_b32_e32 v20, 0xffff0000, v78
	v_add_f32_e32 v18, 1.0, v22
	v_mul_f32_e32 v20, 0xbfb8aa3b, v20
	v_lshlrev_b32_e32 v21, 16, v79
	v_rcp_f32_e32 v18, v18
	v_exp_f32_e32 v20, v20
	v_mul_f32_e32 v21, 0xbfb8aa3b, v21
	v_exp_f32_e32 v21, v21
	v_lshlrev_b32_e32 v19, 16, v74
	v_fmac_f32_e32 v19, v14, v18
	v_add_f32_e32 v14, 1.0, v20
	v_rcp_f32_e32 v14, v14
	v_add_f32_e32 v18, 1.0, v21
	v_rcp_f32_e32 v18, v18
	v_and_b32_e32 v20, 0xffff0000, v74
	v_fmac_f32_e32 v20, v15, v14
	v_lshlrev_b32_e32 v14, 16, v75
	v_and_b32_e32 v15, 0xffff0000, v79
	v_fmac_f32_e32 v14, v16, v18
	v_mul_f32_e32 v15, 0xbfb8aa3b, v15
	v_lshlrev_b32_e32 v16, 16, v80
	v_exp_f32_e32 v15, v15
	v_mul_f32_e32 v16, 0xbfb8aa3b, v16
	v_exp_f32_e32 v16, v16
	v_and_b32_e32 v21, 0xffff0000, v80
	v_add_f32_e32 v15, 1.0, v15
	v_rcp_f32_e32 v15, v15
	v_add_f32_e32 v16, 1.0, v16
	v_mul_f32_e32 v21, 0xbfb8aa3b, v21
	v_rcp_f32_e32 v16, v16
	v_exp_f32_e32 v21, v21
	v_and_b32_e32 v18, 0xffff0000, v75
	v_fmac_f32_e32 v18, v17, v15
	v_lshlrev_b32_e32 v15, 16, v76
	v_fmac_f32_e32 v15, v10, v16
	v_add_f32_e32 v10, 1.0, v21
	v_and_b32_e32 v21, 0xffff0000, v81
	v_mul_f32_e32 v21, 0xbfb8aa3b, v21
	v_rcp_f32_e32 v10, v10
	v_lshlrev_b32_e32 v17, 16, v81
	v_exp_f32_e32 v21, v21
	v_mul_f32_e32 v17, 0xbfb8aa3b, v17
	v_exp_f32_e32 v17, v17
	v_and_b32_e32 v16, 0xffff0000, v76
	v_fmac_f32_e32 v16, v11, v10
	v_add_f32_e32 v11, 1.0, v21
	v_rcp_f32_e32 v11, v11
	v_add_f32_e32 v10, 1.0, v17
	v_rcp_f32_e32 v10, v10
	v_and_b32_e32 v21, 0xffff0000, v77
	v_fmac_f32_e32 v21, v13, v11
	s_waitcnt vmcnt(6)
	v_lshlrev_b32_e32 v13, 16, v70
	v_lshlrev_b32_e32 v17, 16, v77
	v_mul_f32_e32 v13, 0xbfb8aa3b, v13
	v_fmac_f32_e32 v17, v12, v10
	v_cvt_pk_bf16_f32 v10, v19, v20
	v_cvt_pk_bf16_f32 v11, v14, v18
	v_cvt_pk_bf16_f32 v12, v15, v16
	v_exp_f32_e32 v16, v13
	v_lshl_add_u64 v[14:15], v[132:133], 1, v[218:219]
	v_cvt_pk_bf16_f32 v13, v17, v21
	global_store_dwordx4 v[14:15], v[10:13], off
	s_nop 1
	v_and_b32_e32 v12, 0xffff0000, v70
	v_add_f32_e32 v10, 1.0, v16
	v_mul_f32_e32 v12, 0xbfb8aa3b, v12
	v_lshlrev_b32_e32 v13, 16, v71
	v_rcp_f32_e32 v10, v10
	v_exp_f32_e32 v12, v12
	v_mul_f32_e32 v13, 0xbfb8aa3b, v13
	v_exp_f32_e32 v13, v13
	v_lshlrev_b32_e32 v11, 16, v66
	v_fmac_f32_e32 v11, v6, v10
	v_add_f32_e32 v6, 1.0, v12
	v_rcp_f32_e32 v6, v6
	v_add_f32_e32 v10, 1.0, v13
	v_rcp_f32_e32 v10, v10
	v_and_b32_e32 v12, 0xffff0000, v66
	v_fmac_f32_e32 v12, v7, v6
	v_lshlrev_b32_e32 v6, 16, v67
	v_and_b32_e32 v7, 0xffff0000, v71
	v_fmac_f32_e32 v6, v8, v10
	v_mul_f32_e32 v7, 0xbfb8aa3b, v7
	v_lshlrev_b32_e32 v8, 16, v72
	v_exp_f32_e32 v7, v7
	v_mul_f32_e32 v8, 0xbfb8aa3b, v8
	v_exp_f32_e32 v8, v8
	v_and_b32_e32 v13, 0xffff0000, v72
	v_add_f32_e32 v7, 1.0, v7
	v_rcp_f32_e32 v7, v7
	v_add_f32_e32 v8, 1.0, v8
	v_mul_f32_e32 v13, 0xbfb8aa3b, v13
	v_rcp_f32_e32 v8, v8
	v_exp_f32_e32 v13, v13
	v_and_b32_e32 v10, 0xffff0000, v67
	v_fmac_f32_e32 v10, v9, v7
	v_lshlrev_b32_e32 v7, 16, v68
	v_fmac_f32_e32 v7, v2, v8
	v_add_f32_e32 v2, 1.0, v13
	v_lshlrev_b32_e32 v9, 16, v73
	v_and_b32_e32 v13, 0xffff0000, v73
	v_mul_f32_e32 v9, 0xbfb8aa3b, v9
	v_mul_f32_e32 v13, 0xbfb8aa3b, v13
	v_rcp_f32_e32 v2, v2
	v_exp_f32_e32 v9, v9
	v_exp_f32_e32 v13, v13
	v_and_b32_e32 v8, 0xffff0000, v68
	v_fmac_f32_e32 v8, v3, v2
	v_add_f32_e32 v2, 1.0, v9
	v_add_f32_e32 v3, 1.0, v13
	v_rcp_f32_e32 v2, v2
	v_rcp_f32_e32 v3, v3
	v_lshlrev_b32_e32 v9, 16, v69
	v_and_b32_e32 v13, 0xffff0000, v69
	v_fmac_f32_e32 v9, v4, v2
	v_fmac_f32_e32 v13, v5, v3
	v_cvt_pk_bf16_f32 v2, v11, v12
	v_cvt_pk_bf16_f32 v3, v6, v10
	v_cvt_pk_bf16_f32 v4, v7, v8
	v_cvt_pk_bf16_f32 v5, v9, v13
	global_store_dwordx4 v[14:15], v[2:5], off offset:256
	s_setprio 0
	s_cbranch_vccnz .LBB0_2222
	s_andn2_b64 vcc, exec, s[4:5]
	s_cbranch_vccnz .LBB0_2221
	s_barrier
	s_branch .LBB0_2221
